# attention epilogue: permlane32_swap + four dwordx4 stores instead of eight dwordx2; reference-move test trimmed to one compare
# baseline (speedup 1.0000x reference)
.LBB0_439:
	v_cmp_lt_i32_e32 vcc, v138, v139
	v_mov_b32_e32 v36, v136
	s_addk_i32 s80, 0xff00
	v_cndmask_b32_e32 v34, v137, v138, vcc
	v_lshlrev_b32_e32 v34, 2, v34
	ds_bpermute_b32 v34, v34, v79
	s_addk_i32 s81, 0x100
	s_waitcnt lgkmcnt(0)
	v_add_f32_e32 v34, v79, v34
	v_div_scale_f32 v35, s[0:1], v34, v34, 1.0
	v_rcp_f32_e32 v37, v35
	v_div_scale_f32 v38, vcc, 1.0, v34, 1.0
	v_fma_f32 v39, -v35, v37, 1.0
	v_fmac_f32_e32 v37, v39, v37
	v_mul_f32_e32 v39, v38, v37
	v_fma_f32 v40, -v35, v39, v38
	v_fmac_f32_e32 v39, v40, v37
	v_fma_f32 v35, -v35, v39, v38
	v_div_fmas_f32 v35, v35, v37, v39
	v_div_fixup_f32 v37, v35, v34, 1.0
	v_ashrrev_i32_e32 v34, 1, v36
	v_bfi_b32 v34, s73, v34, v36
	v_ashrrev_i32_e32 v35, 31, v34
	v_lshl_add_u64 v[34:35], s[48:49], 0, v[34:35]
	v_lshlrev_b64 v[34:35], 10, v[34:35]
	v_lshrrev_b32_e32 v36, 1, v36
	v_lshl_add_u64 v[34:35], s[46:47], 0, v[34:35]
	v_and_b32_e32 v132, 16, v36
	v_mul_f32_e32 v2, v2, v37
	v_mul_f32_e32 v3, v3, v37
	v_mul_f32_e32 v4, v4, v37
	v_mul_f32_e32 v5, v5, v37
	v_mul_f32_e32 v6, v6, v37
	v_mul_f32_e32 v7, v7, v37
	v_mul_f32_e32 v8, v8, v37
	v_mul_f32_e32 v9, v9, v37
	v_mul_f32_e32 v10, v10, v37
	v_mul_f32_e32 v11, v11, v37
	v_mul_f32_e32 v12, v12, v37
	v_mul_f32_e32 v13, v13, v37
	v_mul_f32_e32 v14, v14, v37
	v_mul_f32_e32 v15, v15, v37
	v_mul_f32_e32 v16, v16, v37
	v_mul_f32_e32 v17, v17, v37
	v_mul_f32_e32 v18, v18, v37
	v_mul_f32_e32 v19, v19, v37
	v_mul_f32_e32 v20, v20, v37
	v_mul_f32_e32 v21, v21, v37
	v_mul_f32_e32 v22, v22, v37
	v_mul_f32_e32 v23, v23, v37
	v_mul_f32_e32 v24, v24, v37
	v_mul_f32_e32 v25, v25, v37
	v_mul_f32_e32 v26, v26, v37
	v_mul_f32_e32 v27, v27, v37
	v_mul_f32_e32 v28, v28, v37
	v_mul_f32_e32 v29, v29, v37
	v_mul_f32_e32 v30, v30, v37
	v_mul_f32_e32 v31, v31, v37
	v_mul_f32_e32 v32, v32, v37
	v_mul_f32_e32 v33, v33, v37
	v_lshl_add_u64 v[34:35], v[34:35], 0, v[132:133]
	v_cvt_pk_bf16_f32 v2, v2, v3
	v_cvt_pk_bf16_f32 v3, v4, v5
	v_cvt_pk_bf16_f32 v4, v6, v7
	v_cvt_pk_bf16_f32 v5, v8, v9
	s_nop 1
	v_permlane32_swap_b32_e32 v2, v4
	v_permlane32_swap_b32_e32 v3, v5
	global_store_dwordx4 v[34:35], v[2:5], off
	v_cvt_pk_bf16_f32 v10, v10, v11
	v_cvt_pk_bf16_f32 v11, v12, v13
	v_cvt_pk_bf16_f32 v12, v14, v15
	v_cvt_pk_bf16_f32 v13, v16, v17
	s_nop 1
	v_permlane32_swap_b32_e32 v10, v12
	v_permlane32_swap_b32_e32 v11, v13
	global_store_dwordx4 v[34:35], v[10:13], off offset:32
	v_cvt_pk_bf16_f32 v18, v18, v19
	v_cvt_pk_bf16_f32 v19, v20, v21
	v_cvt_pk_bf16_f32 v20, v22, v23
	v_cvt_pk_bf16_f32 v21, v24, v25
	s_nop 1
	v_permlane32_swap_b32_e32 v18, v20
	v_permlane32_swap_b32_e32 v19, v21
	global_store_dwordx4 v[34:35], v[18:21], off offset:64
	v_cvt_pk_bf16_f32 v26, v26, v27
	v_cvt_pk_bf16_f32 v27, v28, v29
	v_cvt_pk_bf16_f32 v28, v30, v31
	v_cvt_pk_bf16_f32 v29, v32, v33
	s_nop 1
	v_permlane32_swap_b32_e32 v26, v28
	v_permlane32_swap_b32_e32 v27, v29
	global_store_dwordx4 v[34:35], v[26:29], off offset:96
	v_sub_co_u32_e64 v2, s[0:1], s82, 1
	s_nop 0
	v_readfirstlane_b32 s82, v2
	s_and_b64 vcc, exec, s[0:1]
	s_barrier
	s_cbranch_vccnz .LBB0_437

.LBB0_476:
	v_max3_f32 v78, v50, v51, v34
	v_max3_f32 v124, v52, v53, v35
	v_max3_f32 v78, v78, v36, v37
	v_max3_f32 v124, v124, v56, v57
	v_max3_f32 v78, v78, v54, v55
	v_max3_f32 v124, v124, v40, v41
	v_max3_f32 v78, v78, v38, v39
	v_max3_f32 v124, v124, v60, v61
	v_max3_f32 v78, v78, v58, v59
	v_max3_f32 v124, v124, v44, v45
	v_max3_f32 v78, v78, v42, v43
	v_max3_f32 v124, v124, v64, v65
	v_max3_f32 v78, v78, v62, v63
	v_max3_f32 v124, v124, v48, v49
	v_max3_f32 v78, v78, v46, v47
	v_max_f32_e32 v78, v78, v124
	v_mov_b32_e32 v124, v78
	s_nop 1
	v_permlane32_swap_b32_e32 v78, v124
	v_max_f32_e32 v78, v78, v124
	v_cmp_lt_f32_e32 vcc, s72, v78
	s_cbranch_vccz .LBB0_464
	s_nop 1
	v_cndmask_b32_e32 v78, 0, v78, vcc
	v_exp_f32_e64 v124, -v78
	v_pk_add_f32 v[50:51], v[50:51], v[78:79] op_sel_hi:[1,0] neg_lo:[0,1] neg_hi:[0,1]
	v_pk_add_f32 v[34:35], v[34:35], v[78:79] op_sel_hi:[1,0] neg_lo:[0,1] neg_hi:[0,1]
	v_pk_add_f32 v[52:53], v[52:53], v[78:79] op_sel_hi:[1,0] neg_lo:[0,1] neg_hi:[0,1]
	v_pk_add_f32 v[36:37], v[36:37], v[78:79] op_sel_hi:[1,0] neg_lo:[0,1] neg_hi:[0,1]
	v_pk_add_f32 v[54:55], v[54:55], v[78:79] op_sel_hi:[1,0] neg_lo:[0,1] neg_hi:[0,1]
	v_pk_add_f32 v[38:39], v[38:39], v[78:79] op_sel_hi:[1,0] neg_lo:[0,1] neg_hi:[0,1]
	v_pk_add_f32 v[56:57], v[56:57], v[78:79] op_sel_hi:[1,0] neg_lo:[0,1] neg_hi:[0,1]
	v_pk_add_f32 v[40:41], v[40:41], v[78:79] op_sel_hi:[1,0] neg_lo:[0,1] neg_hi:[0,1]
	v_pk_add_f32 v[58:59], v[58:59], v[78:79] op_sel_hi:[1,0] neg_lo:[0,1] neg_hi:[0,1]
	v_pk_add_f32 v[42:43], v[42:43], v[78:79] op_sel_hi:[1,0] neg_lo:[0,1] neg_hi:[0,1]
	v_pk_add_f32 v[60:61], v[60:61], v[78:79] op_sel_hi:[1,0] neg_lo:[0,1] neg_hi:[0,1]
	v_pk_add_f32 v[44:45], v[44:45], v[78:79] op_sel_hi:[1,0] neg_lo:[0,1] neg_hi:[0,1]
	v_pk_add_f32 v[62:63], v[62:63], v[78:79] op_sel_hi:[1,0] neg_lo:[0,1] neg_hi:[0,1]
	v_pk_add_f32 v[46:47], v[46:47], v[78:79] op_sel_hi:[1,0] neg_lo:[0,1] neg_hi:[0,1]
	v_pk_add_f32 v[64:65], v[64:65], v[78:79] op_sel_hi:[1,0] neg_lo:[0,1] neg_hi:[0,1]
	v_pk_add_f32 v[48:49], v[48:49], v[78:79] op_sel_hi:[1,0] neg_lo:[0,1] neg_hi:[0,1]
	v_pk_mul_f32 v[16:17], v[16:17], v[124:125] op_sel_hi:[1,0]
	v_pk_mul_f32 v[14:15], v[14:15], v[124:125] op_sel_hi:[1,0]
	v_pk_mul_f32 v[12:13], v[12:13], v[124:125] op_sel_hi:[1,0]
	v_pk_mul_f32 v[10:11], v[10:11], v[124:125] op_sel_hi:[1,0]
	v_pk_mul_f32 v[8:9], v[8:9], v[124:125] op_sel_hi:[1,0]
	v_pk_mul_f32 v[6:7], v[6:7], v[124:125] op_sel_hi:[1,0]
	v_pk_mul_f32 v[4:5], v[4:5], v[124:125] op_sel_hi:[1,0]
	v_pk_mul_f32 v[2:3], v[2:3], v[124:125] op_sel_hi:[1,0]
	v_pk_mul_f32 v[32:33], v[32:33], v[124:125] op_sel_hi:[1,0]
	v_pk_mul_f32 v[30:31], v[30:31], v[124:125] op_sel_hi:[1,0]
	v_pk_mul_f32 v[28:29], v[28:29], v[124:125] op_sel_hi:[1,0]
	v_pk_mul_f32 v[26:27], v[26:27], v[124:125] op_sel_hi:[1,0]
	v_pk_mul_f32 v[24:25], v[24:25], v[124:125] op_sel_hi:[1,0]
	v_pk_mul_f32 v[22:23], v[22:23], v[124:125] op_sel_hi:[1,0]
	v_pk_mul_f32 v[20:21], v[20:21], v[124:125] op_sel_hi:[1,0]
	v_pk_mul_f32 v[18:19], v[18:19], v[124:125] op_sel_hi:[1,0]
	v_add_f32_e32 v153, v153, v78
	v_mul_f32_e32 v79, v79, v124
	s_branch .LBB0_464
